# hand-written leaner SwiGLU epilogue body for FFN-up (packed multiplies, saddr stores) on top of the previous version
# speedup vs baseline: 1.0010x; 1.0010x over previous
; __device__ __forceinline__ unsigned cvt_pk_bf16(float lo, float hi) { unsigned r; asm volatile("v_cvt_pk_bf16_f32 %0, %1, %2" : "=v"(r) : "v"(lo), "v"(hi)); return r; }
;     __device__ __forceinline__ void operator()(f32x4 (&acc)[2][2][4][2], const Unit& u, int wr, int wc, LAS unsigned char* lds, int& rs_pm) const {
;     ...
;                 const float r = rs[ai][m], rsn = r * -1.4426950408889634f, rs2 = r * r; float o[8];
;                 f32x4 av[2], gu[2];
; #pragma unroll
;                 for (int n = 0; n < 2; ++n) { av[n] = acc[ai][0][m][n] * rsn; gu[n] = acc[ai][0][m][n] * acc[ai][1][m][n]; }
; #pragma unroll
;                 for (int n = 0; n < 2; ++n) { zero_acc(acc[ai][0][m][n], zb); zero_acc(acc[ai][1][m][n], zb); }
; #pragma unroll
;                 for (int n = 0; n < 2; ++n)
; #pragma unroll
;                     for (int j = 0; j < 4; ++j) av[n][j] = __builtin_amdgcn_exp2f(av[n][j]);
; #pragma unroll
;                 for (int n = 0; n < 2; ++n) av[n] = av[n] + 1.0f;
; #pragma unroll
;                 for (int n = 0; n < 2; ++n)
; #pragma unroll
;                     for (int j = 0; j < 4; ++j) av[n][j] = __builtin_amdgcn_rcpf(av[n][j]);
; #pragma unroll
;                 for (int n = 0; n < 2; ++n) { const f32x4 q = gu[n] * (av[n] * rs2);
; #pragma unroll
;                     for (int j = 0; j < 4; ++j) o[n * 4 + j] = q[j]; }
;                 u32x4 w; w.x = cvt_pk_bf16(o[0], o[1]); w.y = cvt_pk_bf16(o[2], o[3]); w.z = cvt_pk_bf16(o[4], o[5]); w.w = cvt_pk_bf16(o[6], o[7]);
;                 *(u32x4*)(H + (((size_t)(u.pm * (DFF / 64) + u.pn * 2 + (wc >> 1)) * BM + (wr * 64 + fr + ai * HALF + m * 16)) * 64 + (wc & 1) * 32 + 8 * fq)) = w;
.LBB0_220:
	s_waitcnt lgkmcnt(0)
	v_lshlrev_b32_e32 v136, 7, v162
	v_lshl_or_b32 v136, v158, 1, v136
	v_mov_b32_e32 v132, v1
	v_mov_b32_e32 v133, v1
	v_mov_b32_e32 v134, v1
	v_mov_b32_e32 v135, v1
	s_mul_i32 s100, s86, 0x58
	s_lshl_b32 s101, s85, 1
	s_add_i32 s100, s100, s101
	s_or_b32 s100, s100, s82
	s_ashr_i32 s101, s100, 31
	s_lshl_b64 s[100:101], s[100:101], 15
	s_add_u32 s98, s76, s100
	s_addc_u32 s99, s77, s101
	s_add_u32 s98, s98, s30
	s_addc_u32 s99, s99, s31
	s_lshl_b32 s100, s78, 7
	s_add_u32 s98, s98, s100
	s_addc_u32 s99, s99, 0
	v_mul_f32_e32 v138, 0xbfb8aa3b, v156
	v_mul_f32_e32 v158, v156, v156
	v_pk_mul_f32 v[162:163], v[88:89], v[138:139] op_sel_hi:[1,0]
	v_pk_mul_f32 v[164:165], v[90:91], v[138:139] op_sel_hi:[1,0]
	v_pk_mul_f32 v[166:167], v[124:125], v[138:139] op_sel_hi:[1,0]
	v_pk_mul_f32 v[168:169], v[126:127], v[138:139] op_sel_hi:[1,0]
	v_pk_mul_f32 v[170:171], v[88:89], v[80:81]
	v_pk_mul_f32 v[172:173], v[90:91], v[82:83]
	v_pk_mul_f32 v[174:175], v[124:125], v[128:129]
	v_pk_mul_f32 v[176:177], v[126:127], v[130:131]
	v_exp_f32_e32 v162, v162
	v_exp_f32_e32 v163, v163
	v_exp_f32_e32 v164, v164
	v_exp_f32_e32 v165, v165
	v_exp_f32_e32 v166, v166
	v_exp_f32_e32 v167, v167
	v_exp_f32_e32 v168, v168
	v_exp_f32_e32 v169, v169
	v_mfma_f32_16x16x32_bf16 v[88:91], v[132:135], v[132:135], 0
	v_mfma_f32_16x16x32_bf16 v[124:127], v[132:135], v[132:135], 0
	v_pk_add_f32 v[162:163], v[162:163], 1.0 op_sel_hi:[1,0]
	v_pk_add_f32 v[164:165], v[164:165], 1.0 op_sel_hi:[1,0]
	v_pk_add_f32 v[166:167], v[166:167], 1.0 op_sel_hi:[1,0]
	v_pk_add_f32 v[168:169], v[168:169], 1.0 op_sel_hi:[1,0]
	v_rcp_f32_e32 v162, v162
	v_rcp_f32_e32 v163, v163
	v_rcp_f32_e32 v164, v164
	v_rcp_f32_e32 v165, v165
	v_rcp_f32_e32 v166, v166
	v_rcp_f32_e32 v167, v167
	v_rcp_f32_e32 v168, v168
	v_rcp_f32_e32 v169, v169
	v_mfma_f32_16x16x32_bf16 v[80:83], v[132:135], v[132:135], 0
	v_mfma_f32_16x16x32_bf16 v[128:131], v[132:135], v[132:135], 0
	v_pk_mul_f32 v[170:171], v[170:171], v[158:159] op_sel_hi:[1,0]
	v_pk_mul_f32 v[172:173], v[172:173], v[158:159] op_sel_hi:[1,0]
	v_pk_mul_f32 v[174:175], v[174:175], v[158:159] op_sel_hi:[1,0]
	v_pk_mul_f32 v[176:177], v[176:177], v[158:159] op_sel_hi:[1,0]
	v_pk_mul_f32 v[170:171], v[170:171], v[162:163]
	v_pk_mul_f32 v[172:173], v[172:173], v[164:165]
	v_pk_mul_f32 v[174:175], v[174:175], v[166:167]
	v_pk_mul_f32 v[176:177], v[176:177], v[168:169]
	v_cvt_pk_bf16_f32 v178, v170, v171
	v_cvt_pk_bf16_f32 v179, v172, v173
	v_cvt_pk_bf16_f32 v180, v174, v175
	v_cvt_pk_bf16_f32 v181, v176, v177
	global_store_dwordx4 v136, v[178:181], s[98:99]
	v_mul_f32_e32 v138, 0xbfb8aa3b, v157
	v_mul_f32_e32 v158, v157, v157
	v_pk_mul_f32 v[162:163], v[52:53], v[138:139] op_sel_hi:[1,0]
	v_pk_mul_f32 v[164:165], v[54:55], v[138:139] op_sel_hi:[1,0]
	v_pk_mul_f32 v[166:167], v[120:121], v[138:139] op_sel_hi:[1,0]
	v_pk_mul_f32 v[168:169], v[122:123], v[138:139] op_sel_hi:[1,0]
	v_pk_mul_f32 v[170:171], v[52:53], v[68:69]
	v_pk_mul_f32 v[172:173], v[54:55], v[70:71]
	v_pk_mul_f32 v[174:175], v[120:121], v[108:109]
	v_pk_mul_f32 v[176:177], v[122:123], v[110:111]
	v_exp_f32_e32 v162, v162
	v_exp_f32_e32 v163, v163
	v_exp_f32_e32 v164, v164
	v_exp_f32_e32 v165, v165
	v_exp_f32_e32 v166, v166
	v_exp_f32_e32 v167, v167
	v_exp_f32_e32 v168, v168
	v_exp_f32_e32 v169, v169
	v_mfma_f32_16x16x32_bf16 v[52:55], v[132:135], v[132:135], 0
	v_mfma_f32_16x16x32_bf16 v[120:123], v[132:135], v[132:135], 0
	v_pk_add_f32 v[162:163], v[162:163], 1.0 op_sel_hi:[1,0]
	v_pk_add_f32 v[164:165], v[164:165], 1.0 op_sel_hi:[1,0]
	v_pk_add_f32 v[166:167], v[166:167], 1.0 op_sel_hi:[1,0]
	v_pk_add_f32 v[168:169], v[168:169], 1.0 op_sel_hi:[1,0]
	v_rcp_f32_e32 v162, v162
	v_rcp_f32_e32 v163, v163
	v_rcp_f32_e32 v164, v164
	v_rcp_f32_e32 v165, v165
	v_rcp_f32_e32 v166, v166
	v_rcp_f32_e32 v167, v167
	v_rcp_f32_e32 v168, v168
	v_rcp_f32_e32 v169, v169
	v_mfma_f32_16x16x32_bf16 v[68:71], v[132:135], v[132:135], 0
	v_mfma_f32_16x16x32_bf16 v[108:111], v[132:135], v[132:135], 0
	v_pk_mul_f32 v[170:171], v[170:171], v[158:159] op_sel_hi:[1,0]
	v_pk_mul_f32 v[172:173], v[172:173], v[158:159] op_sel_hi:[1,0]
	v_pk_mul_f32 v[174:175], v[174:175], v[158:159] op_sel_hi:[1,0]
	v_pk_mul_f32 v[176:177], v[176:177], v[158:159] op_sel_hi:[1,0]
	v_pk_mul_f32 v[170:171], v[170:171], v[162:163]
	v_pk_mul_f32 v[172:173], v[172:173], v[164:165]
	v_pk_mul_f32 v[174:175], v[174:175], v[166:167]
	v_pk_mul_f32 v[176:177], v[176:177], v[168:169]
	v_cvt_pk_bf16_f32 v182, v170, v171
	v_cvt_pk_bf16_f32 v183, v172, v173
	v_cvt_pk_bf16_f32 v184, v174, v175
	v_cvt_pk_bf16_f32 v185, v176, v177
	global_store_dwordx4 v136, v[182:185], s[98:99] offset:2048
	v_mul_f32_e32 v138, 0xbfb8aa3b, v154
	v_mul_f32_e32 v158, v154, v154
	v_pk_mul_f32 v[162:163], v[40:41], v[138:139] op_sel_hi:[1,0]
	v_pk_mul_f32 v[164:165], v[42:43], v[138:139] op_sel_hi:[1,0]
	v_pk_mul_f32 v[166:167], v[116:117], v[138:139] op_sel_hi:[1,0]
	v_pk_mul_f32 v[168:169], v[118:119], v[138:139] op_sel_hi:[1,0]
	v_pk_mul_f32 v[170:171], v[40:41], v[60:61]
	v_pk_mul_f32 v[172:173], v[42:43], v[62:63]
	v_pk_mul_f32 v[174:175], v[116:117], v[104:105]
	v_pk_mul_f32 v[176:177], v[118:119], v[106:107]
	v_exp_f32_e32 v162, v162
	v_exp_f32_e32 v163, v163
	v_exp_f32_e32 v164, v164
	v_exp_f32_e32 v165, v165
	v_exp_f32_e32 v166, v166
	v_exp_f32_e32 v167, v167
	v_exp_f32_e32 v168, v168
	v_exp_f32_e32 v169, v169
	v_mfma_f32_16x16x32_bf16 v[40:43], v[132:135], v[132:135], 0
	v_mfma_f32_16x16x32_bf16 v[116:119], v[132:135], v[132:135], 0
	v_pk_add_f32 v[162:163], v[162:163], 1.0 op_sel_hi:[1,0]
	v_pk_add_f32 v[164:165], v[164:165], 1.0 op_sel_hi:[1,0]
; __device__ __forceinline__ unsigned cvt_pk_bf16(float lo, float hi) { unsigned r; asm volatile("v_cvt_pk_bf16_f32 %0, %1, %2" : "=v"(r) : "v"(lo), "v"(hi)); return r; }
;     __device__ __forceinline__ void operator()(f32x4 (&acc)[2][2][4][2], const Unit& u, int wr, int wc, LAS unsigned char* lds, int& rs_pm) const {
;     ...
;                 const float r = rs[ai][m], rsn = r * -1.4426950408889634f, rs2 = r * r; float o[8];
;                 f32x4 av[2], gu[2];
; #pragma unroll
;                 for (int n = 0; n < 2; ++n) { av[n] = acc[ai][0][m][n] * rsn; gu[n] = acc[ai][0][m][n] * acc[ai][1][m][n]; }
; #pragma unroll
;                 for (int n = 0; n < 2; ++n) { zero_acc(acc[ai][0][m][n], zb); zero_acc(acc[ai][1][m][n], zb); }
; #pragma unroll
;                 for (int n = 0; n < 2; ++n)
; #pragma unroll
;                     for (int j = 0; j < 4; ++j) av[n][j] = __builtin_amdgcn_exp2f(av[n][j]);
; #pragma unroll
;                 for (int n = 0; n < 2; ++n) av[n] = av[n] + 1.0f;
; #pragma unroll
;                 for (int n = 0; n < 2; ++n)
; #pragma unroll
;                     for (int j = 0; j < 4; ++j) av[n][j] = __builtin_amdgcn_rcpf(av[n][j]);
; #pragma unroll
;                 for (int n = 0; n < 2; ++n) { const f32x4 q = gu[n] * (av[n] * rs2);
; #pragma unroll
;                     for (int j = 0; j < 4; ++j) o[n * 4 + j] = q[j]; }
;                 u32x4 w; w.x = cvt_pk_bf16(o[0], o[1]); w.y = cvt_pk_bf16(o[2], o[3]); w.z = cvt_pk_bf16(o[4], o[5]); w.w = cvt_pk_bf16(o[6], o[7]);
;                 *(u32x4*)(H + (((size_t)(u.pm * (DFF / 64) + u.pn * 2 + (wc >> 1)) * BM + (wr * 64 + fr + ai * HALF + m * 16)) * 64 + (wc & 1) * 32 + 8 * fq)) = w;
	v_pk_add_f32 v[166:167], v[166:167], 1.0 op_sel_hi:[1,0]
	v_pk_add_f32 v[168:169], v[168:169], 1.0 op_sel_hi:[1,0]
	v_rcp_f32_e32 v162, v162
	v_rcp_f32_e32 v163, v163
	v_rcp_f32_e32 v164, v164
	v_rcp_f32_e32 v165, v165
	v_rcp_f32_e32 v166, v166
	v_rcp_f32_e32 v167, v167
	v_rcp_f32_e32 v168, v168
	v_rcp_f32_e32 v169, v169
	v_mfma_f32_16x16x32_bf16 v[60:63], v[132:135], v[132:135], 0
	v_mfma_f32_16x16x32_bf16 v[104:107], v[132:135], v[132:135], 0
	v_pk_mul_f32 v[170:171], v[170:171], v[158:159] op_sel_hi:[1,0]
	v_pk_mul_f32 v[172:173], v[172:173], v[158:159] op_sel_hi:[1,0]
	v_pk_mul_f32 v[174:175], v[174:175], v[158:159] op_sel_hi:[1,0]
	v_pk_mul_f32 v[176:177], v[176:177], v[158:159] op_sel_hi:[1,0]
	v_pk_mul_f32 v[170:171], v[170:171], v[162:163]
	v_pk_mul_f32 v[172:173], v[172:173], v[164:165]
	v_pk_mul_f32 v[174:175], v[174:175], v[166:167]
	v_pk_mul_f32 v[176:177], v[176:177], v[168:169]
	v_cvt_pk_bf16_f32 v178, v170, v171
	v_cvt_pk_bf16_f32 v179, v172, v173
	v_cvt_pk_bf16_f32 v180, v174, v175
	v_cvt_pk_bf16_f32 v181, v176, v177
	s_add_u32 s100, s98, 0x1000
	s_addc_u32 s101, s99, 0
	global_store_dwordx4 v136, v[178:181], s[100:101]
	v_mul_f32_e32 v138, 0xbfb8aa3b, v155
	v_mul_f32_e32 v158, v155, v155
	v_pk_mul_f32 v[162:163], v[36:37], v[138:139] op_sel_hi:[1,0]
	v_pk_mul_f32 v[164:165], v[38:39], v[138:139] op_sel_hi:[1,0]
	v_pk_mul_f32 v[166:167], v[112:113], v[138:139] op_sel_hi:[1,0]
	v_pk_mul_f32 v[168:169], v[114:115], v[138:139] op_sel_hi:[1,0]
	v_pk_mul_f32 v[170:171], v[36:37], v[48:49]
	v_pk_mul_f32 v[172:173], v[38:39], v[50:51]
	v_pk_mul_f32 v[174:175], v[112:113], v[100:101]
	v_pk_mul_f32 v[176:177], v[114:115], v[102:103]
	v_exp_f32_e32 v162, v162
	v_exp_f32_e32 v163, v163
	v_exp_f32_e32 v164, v164
	v_exp_f32_e32 v165, v165
	v_exp_f32_e32 v166, v166
	v_exp_f32_e32 v167, v167
	v_exp_f32_e32 v168, v168
	v_exp_f32_e32 v169, v169
	v_mfma_f32_16x16x32_bf16 v[36:39], v[132:135], v[132:135], 0
	v_mfma_f32_16x16x32_bf16 v[112:115], v[132:135], v[132:135], 0
	v_pk_add_f32 v[162:163], v[162:163], 1.0 op_sel_hi:[1,0]
	v_pk_add_f32 v[164:165], v[164:165], 1.0 op_sel_hi:[1,0]
	v_pk_add_f32 v[166:167], v[166:167], 1.0 op_sel_hi:[1,0]
	v_pk_add_f32 v[168:169], v[168:169], 1.0 op_sel_hi:[1,0]
	v_rcp_f32_e32 v162, v162
	v_rcp_f32_e32 v163, v163
	v_rcp_f32_e32 v164, v164
	v_rcp_f32_e32 v165, v165
	v_rcp_f32_e32 v166, v166
	v_rcp_f32_e32 v167, v167
	v_rcp_f32_e32 v168, v168
	v_rcp_f32_e32 v169, v169
	v_mfma_f32_16x16x32_bf16 v[48:51], v[132:135], v[132:135], 0
	v_mfma_f32_16x16x32_bf16 v[100:103], v[132:135], v[132:135], 0
	v_pk_mul_f32 v[170:171], v[170:171], v[158:159] op_sel_hi:[1,0]
	v_pk_mul_f32 v[172:173], v[172:173], v[158:159] op_sel_hi:[1,0]
	v_pk_mul_f32 v[174:175], v[174:175], v[158:159] op_sel_hi:[1,0]
	v_pk_mul_f32 v[176:177], v[176:177], v[158:159] op_sel_hi:[1,0]
	v_pk_mul_f32 v[170:171], v[170:171], v[162:163]
	v_pk_mul_f32 v[172:173], v[172:173], v[164:165]
	v_pk_mul_f32 v[174:175], v[174:175], v[166:167]
	v_pk_mul_f32 v[176:177], v[176:177], v[168:169]
	v_cvt_pk_bf16_f32 v182, v170, v171
	v_cvt_pk_bf16_f32 v183, v172, v173
	v_cvt_pk_bf16_f32 v184, v174, v175
	v_cvt_pk_bf16_f32 v185, v176, v177
	s_add_u32 s100, s98, 0x1000
	s_addc_u32 s101, s99, 0
	global_store_dwordx4 v136, v[182:185], s[100:101] offset:2048
	v_mul_f32_e32 v138, 0xbfb8aa3b, v152
	v_mul_f32_e32 v158, v152, v152
	v_pk_mul_f32 v[162:163], v[24:25], v[138:139] op_sel_hi:[1,0]
	v_pk_mul_f32 v[164:165], v[26:27], v[138:139] op_sel_hi:[1,0]
	v_pk_mul_f32 v[166:167], v[92:93], v[138:139] op_sel_hi:[1,0]
	v_pk_mul_f32 v[168:169], v[94:95], v[138:139] op_sel_hi:[1,0]
	v_pk_mul_f32 v[170:171], v[24:25], v[32:33]
	v_pk_mul_f32 v[172:173], v[26:27], v[34:35]
	v_pk_mul_f32 v[174:175], v[92:93], v[72:73]
	v_pk_mul_f32 v[176:177], v[94:95], v[74:75]
	v_exp_f32_e32 v162, v162
	v_exp_f32_e32 v163, v163
	v_exp_f32_e32 v164, v164
	v_exp_f32_e32 v165, v165
	v_exp_f32_e32 v166, v166
	v_exp_f32_e32 v167, v167
	v_exp_f32_e32 v168, v168
	v_exp_f32_e32 v169, v169
	v_mfma_f32_16x16x32_bf16 v[24:27], v[132:135], v[132:135], 0
	v_mfma_f32_16x16x32_bf16 v[92:95], v[132:135], v[132:135], 0
	v_pk_add_f32 v[162:163], v[162:163], 1.0 op_sel_hi:[1,0]
	v_pk_add_f32 v[164:165], v[164:165], 1.0 op_sel_hi:[1,0]
	v_pk_add_f32 v[166:167], v[166:167], 1.0 op_sel_hi:[1,0]
	v_pk_add_f32 v[168:169], v[168:169], 1.0 op_sel_hi:[1,0]
	v_rcp_f32_e32 v162, v162
	v_rcp_f32_e32 v163, v163
	v_rcp_f32_e32 v164, v164
	v_rcp_f32_e32 v165, v165
	v_rcp_f32_e32 v166, v166
	v_rcp_f32_e32 v167, v167
	v_rcp_f32_e32 v168, v168
	v_rcp_f32_e32 v169, v169
	v_mfma_f32_16x16x32_bf16 v[32:35], v[132:135], v[132:135], 0
	v_mfma_f32_16x16x32_bf16 v[72:75], v[132:135], v[132:135], 0
	v_pk_mul_f32 v[170:171], v[170:171], v[158:159] op_sel_hi:[1,0]
	v_pk_mul_f32 v[172:173], v[172:173], v[158:159] op_sel_hi:[1,0]
	v_pk_mul_f32 v[174:175], v[174:175], v[158:159] op_sel_hi:[1,0]
	v_pk_mul_f32 v[176:177], v[176:177], v[158:159] op_sel_hi:[1,0]
	v_pk_mul_f32 v[170:171], v[170:171], v[162:163]
	v_pk_mul_f32 v[172:173], v[172:173], v[164:165]
	v_pk_mul_f32 v[174:175], v[174:175], v[166:167]
	v_pk_mul_f32 v[176:177], v[176:177], v[168:169]
	v_cvt_pk_bf16_f32 v178, v170, v171
	v_cvt_pk_bf16_f32 v179, v172, v173
	v_cvt_pk_bf16_f32 v180, v174, v175
	v_cvt_pk_bf16_f32 v181, v176, v177
	s_add_u32 s100, s98, 0x4000
	s_addc_u32 s101, s99, 0
	global_store_dwordx4 v136, v[178:181], s[100:101]
	v_mul_f32_e32 v138, 0xbfb8aa3b, v153
	v_mul_f32_e32 v158, v153, v153
	v_pk_mul_f32 v[162:163], v[16:17], v[138:139] op_sel_hi:[1,0]
	v_pk_mul_f32 v[164:165], v[18:19], v[138:139] op_sel_hi:[1,0]
	v_pk_mul_f32 v[166:167], v[84:85], v[138:139] op_sel_hi:[1,0]
; __device__ __forceinline__ unsigned cvt_pk_bf16(float lo, float hi) { unsigned r; asm volatile("v_cvt_pk_bf16_f32 %0, %1, %2" : "=v"(r) : "v"(lo), "v"(hi)); return r; }
;     __device__ __forceinline__ void operator()(f32x4 (&acc)[2][2][4][2], const Unit& u, int wr, int wc, LAS unsigned char* lds, int& rs_pm) const {
;     ...
;                 const float r = rs[ai][m], rsn = r * -1.4426950408889634f, rs2 = r * r; float o[8];
;                 f32x4 av[2], gu[2];
; #pragma unroll
;                 for (int n = 0; n < 2; ++n) { av[n] = acc[ai][0][m][n] * rsn; gu[n] = acc[ai][0][m][n] * acc[ai][1][m][n]; }
; #pragma unroll
;                 for (int n = 0; n < 2; ++n) { zero_acc(acc[ai][0][m][n], zb); zero_acc(acc[ai][1][m][n], zb); }
; #pragma unroll
;                 for (int n = 0; n < 2; ++n)
; #pragma unroll
;                     for (int j = 0; j < 4; ++j) av[n][j] = __builtin_amdgcn_exp2f(av[n][j]);
; #pragma unroll
;                 for (int n = 0; n < 2; ++n) av[n] = av[n] + 1.0f;
; #pragma unroll
;                 for (int n = 0; n < 2; ++n)
; #pragma unroll
;                     for (int j = 0; j < 4; ++j) av[n][j] = __builtin_amdgcn_rcpf(av[n][j]);
; #pragma unroll
;                 for (int n = 0; n < 2; ++n) { const f32x4 q = gu[n] * (av[n] * rs2);
; #pragma unroll
;                     for (int j = 0; j < 4; ++j) o[n * 4 + j] = q[j]; }
;                 u32x4 w; w.x = cvt_pk_bf16(o[0], o[1]); w.y = cvt_pk_bf16(o[2], o[3]); w.z = cvt_pk_bf16(o[4], o[5]); w.w = cvt_pk_bf16(o[6], o[7]);
;                 *(u32x4*)(H + (((size_t)(u.pm * (DFF / 64) + u.pn * 2 + (wc >> 1)) * BM + (wr * 64 + fr + ai * HALF + m * 16)) * 64 + (wc & 1) * 32 + 8 * fq)) = w;
	v_pk_mul_f32 v[168:169], v[86:87], v[138:139] op_sel_hi:[1,0]
	v_pk_mul_f32 v[170:171], v[16:17], v[28:29]
	v_pk_mul_f32 v[172:173], v[18:19], v[30:31]
	v_pk_mul_f32 v[174:175], v[84:85], v[96:97]
	v_pk_mul_f32 v[176:177], v[86:87], v[98:99]
	v_exp_f32_e32 v162, v162
	v_exp_f32_e32 v163, v163
	v_exp_f32_e32 v164, v164
	v_exp_f32_e32 v165, v165
	v_exp_f32_e32 v166, v166
	v_exp_f32_e32 v167, v167
	v_exp_f32_e32 v168, v168
	v_exp_f32_e32 v169, v169
	v_mfma_f32_16x16x32_bf16 v[16:19], v[132:135], v[132:135], 0
	v_mfma_f32_16x16x32_bf16 v[84:87], v[132:135], v[132:135], 0
	v_pk_add_f32 v[162:163], v[162:163], 1.0 op_sel_hi:[1,0]
	v_pk_add_f32 v[164:165], v[164:165], 1.0 op_sel_hi:[1,0]
	v_pk_add_f32 v[166:167], v[166:167], 1.0 op_sel_hi:[1,0]
	v_pk_add_f32 v[168:169], v[168:169], 1.0 op_sel_hi:[1,0]
	v_rcp_f32_e32 v162, v162
	v_rcp_f32_e32 v163, v163
	v_rcp_f32_e32 v164, v164
	v_rcp_f32_e32 v165, v165
	v_rcp_f32_e32 v166, v166
	v_rcp_f32_e32 v167, v167
	v_rcp_f32_e32 v168, v168
	v_rcp_f32_e32 v169, v169
	v_mfma_f32_16x16x32_bf16 v[28:31], v[132:135], v[132:135], 0
	v_mfma_f32_16x16x32_bf16 v[96:99], v[132:135], v[132:135], 0
	v_pk_mul_f32 v[170:171], v[170:171], v[158:159] op_sel_hi:[1,0]
	v_pk_mul_f32 v[172:173], v[172:173], v[158:159] op_sel_hi:[1,0]
	v_pk_mul_f32 v[174:175], v[174:175], v[158:159] op_sel_hi:[1,0]
	v_pk_mul_f32 v[176:177], v[176:177], v[158:159] op_sel_hi:[1,0]
	v_pk_mul_f32 v[170:171], v[170:171], v[162:163]
	v_pk_mul_f32 v[172:173], v[172:173], v[164:165]
	v_pk_mul_f32 v[174:175], v[174:175], v[166:167]
	v_pk_mul_f32 v[176:177], v[176:177], v[168:169]
	v_cvt_pk_bf16_f32 v182, v170, v171
	v_cvt_pk_bf16_f32 v183, v172, v173
	v_cvt_pk_bf16_f32 v184, v174, v175
	v_cvt_pk_bf16_f32 v185, v176, v177
	s_add_u32 s100, s98, 0x4000
	s_addc_u32 s101, s99, 0
	global_store_dwordx4 v136, v[182:185], s[100:101] offset:2048
	v_mul_f32_e32 v138, 0xbfb8aa3b, v2
	v_mul_f32_e32 v158, v2, v2
	v_pk_mul_f32 v[162:163], v[8:9], v[138:139] op_sel_hi:[1,0]
	v_pk_mul_f32 v[164:165], v[10:11], v[138:139] op_sel_hi:[1,0]
	v_pk_mul_f32 v[166:167], v[76:77], v[138:139] op_sel_hi:[1,0]
	v_pk_mul_f32 v[168:169], v[78:79], v[138:139] op_sel_hi:[1,0]
	v_pk_mul_f32 v[170:171], v[8:9], v[20:21]
	v_pk_mul_f32 v[172:173], v[10:11], v[22:23]
	v_pk_mul_f32 v[174:175], v[76:77], v[56:57]
	v_pk_mul_f32 v[176:177], v[78:79], v[58:59]
	v_exp_f32_e32 v162, v162
	v_exp_f32_e32 v163, v163
	v_exp_f32_e32 v164, v164
	v_exp_f32_e32 v165, v165
	v_exp_f32_e32 v166, v166
	v_exp_f32_e32 v167, v167
	v_exp_f32_e32 v168, v168
	v_exp_f32_e32 v169, v169
	v_mfma_f32_16x16x32_bf16 v[8:11], v[132:135], v[132:135], 0
	v_mfma_f32_16x16x32_bf16 v[76:79], v[132:135], v[132:135], 0
	v_pk_add_f32 v[162:163], v[162:163], 1.0 op_sel_hi:[1,0]
	v_pk_add_f32 v[164:165], v[164:165], 1.0 op_sel_hi:[1,0]
	v_pk_add_f32 v[166:167], v[166:167], 1.0 op_sel_hi:[1,0]
	v_pk_add_f32 v[168:169], v[168:169], 1.0 op_sel_hi:[1,0]
	v_rcp_f32_e32 v162, v162
	v_rcp_f32_e32 v163, v163
	v_rcp_f32_e32 v164, v164
	v_rcp_f32_e32 v165, v165
	v_rcp_f32_e32 v166, v166
	v_rcp_f32_e32 v167, v167
	v_rcp_f32_e32 v168, v168
	v_rcp_f32_e32 v169, v169
	v_mfma_f32_16x16x32_bf16 v[20:23], v[132:135], v[132:135], 0
	v_mfma_f32_16x16x32_bf16 v[56:59], v[132:135], v[132:135], 0
	v_pk_mul_f32 v[170:171], v[170:171], v[158:159] op_sel_hi:[1,0]
	v_pk_mul_f32 v[172:173], v[172:173], v[158:159] op_sel_hi:[1,0]
	v_pk_mul_f32 v[174:175], v[174:175], v[158:159] op_sel_hi:[1,0]
	v_pk_mul_f32 v[176:177], v[176:177], v[158:159] op_sel_hi:[1,0]
	v_pk_mul_f32 v[170:171], v[170:171], v[162:163]
	v_pk_mul_f32 v[172:173], v[172:173], v[164:165]
	v_pk_mul_f32 v[174:175], v[174:175], v[166:167]
	v_pk_mul_f32 v[176:177], v[176:177], v[168:169]
	v_cvt_pk_bf16_f32 v178, v170, v171
	v_cvt_pk_bf16_f32 v179, v172, v173
	v_cvt_pk_bf16_f32 v180, v174, v175
	v_cvt_pk_bf16_f32 v181, v176, v177
	s_add_u32 s100, s98, 0x5000
	s_addc_u32 s101, s99, 0
	global_store_dwordx4 v136, v[178:181], s[100:101]
	v_mul_f32_e32 v138, 0xbfb8aa3b, v3
	v_mul_f32_e32 v158, v3, v3
	v_pk_mul_f32 v[162:163], v[4:5], v[138:139] op_sel_hi:[1,0]
	v_pk_mul_f32 v[164:165], v[6:7], v[138:139] op_sel_hi:[1,0]
	v_pk_mul_f32 v[166:167], v[64:65], v[138:139] op_sel_hi:[1,0]
	v_pk_mul_f32 v[168:169], v[66:67], v[138:139] op_sel_hi:[1,0]
	v_pk_mul_f32 v[170:171], v[4:5], v[12:13]
	v_pk_mul_f32 v[172:173], v[6:7], v[14:15]
	v_pk_mul_f32 v[174:175], v[64:65], v[44:45]
	v_pk_mul_f32 v[176:177], v[66:67], v[46:47]
	v_exp_f32_e32 v162, v162
	v_exp_f32_e32 v163, v163
	v_exp_f32_e32 v164, v164
	v_exp_f32_e32 v165, v165
	v_exp_f32_e32 v166, v166
	v_exp_f32_e32 v167, v167
	v_exp_f32_e32 v168, v168
	v_exp_f32_e32 v169, v169
	v_mfma_f32_16x16x32_bf16 v[4:7], v[132:135], v[132:135], 0
	v_mfma_f32_16x16x32_bf16 v[64:67], v[132:135], v[132:135], 0
	v_pk_add_f32 v[162:163], v[162:163], 1.0 op_sel_hi:[1,0]
	v_pk_add_f32 v[164:165], v[164:165], 1.0 op_sel_hi:[1,0]
	v_pk_add_f32 v[166:167], v[166:167], 1.0 op_sel_hi:[1,0]
	v_pk_add_f32 v[168:169], v[168:169], 1.0 op_sel_hi:[1,0]
	v_rcp_f32_e32 v162, v162
	v_rcp_f32_e32 v163, v163
	v_rcp_f32_e32 v164, v164
	v_rcp_f32_e32 v165, v165
	v_rcp_f32_e32 v166, v166
	v_rcp_f32_e32 v167, v167
	v_rcp_f32_e32 v168, v168
	v_rcp_f32_e32 v169, v169
	v_mfma_f32_16x16x32_bf16 v[12:15], v[132:135], v[132:135], 0
	v_mfma_f32_16x16x32_bf16 v[44:47], v[132:135], v[132:135], 0
	v_pk_mul_f32 v[170:171], v[170:171], v[158:159] op_sel_hi:[1,0]
	v_pk_mul_f32 v[172:173], v[172:173], v[158:159] op_sel_hi:[1,0]
	v_pk_mul_f32 v[174:175], v[174:175], v[158:159] op_sel_hi:[1,0]
	v_pk_mul_f32 v[176:177], v[176:177], v[158:159] op_sel_hi:[1,0]
	v_pk_mul_f32 v[170:171], v[170:171], v[162:163]
	v_pk_mul_f32 v[172:173], v[172:173], v[164:165]
	v_pk_mul_f32 v[174:175], v[174:175], v[166:167]
	v_pk_mul_f32 v[176:177], v[176:177], v[168:169]
	v_cvt_pk_bf16_f32 v182, v170, v171
	v_cvt_pk_bf16_f32 v183, v172, v173
	v_cvt_pk_bf16_f32 v184, v174, v175
	v_cvt_pk_bf16_f32 v185, v176, v177
	s_add_u32 s100, s98, 0x5000
	s_addc_u32 s101, s99, 0
	global_store_dwordx4 v136, v[182:185], s[100:101] offset:2048
	s_mov_b64 s[48:49], -1
	s_andn2_b64 vcc, exec, s[40:41]
	s_cbranch_vccnz .LBB0_207
	s_andn2_b64 vcc, exec, s[10:11]
	s_cbranch_vccnz .LBB0_206
	s_barrier
	s_branch .LBB0_206

; __global__ void __launch_bounds__(512, 2) fwd_kernel(Args args) {
	.amdhsa_kernel _Z10fwd_kernel4Args
		.amdhsa_group_segment_fixed_size 0
		.amdhsa_private_segment_fixed_size 0
		.amdhsa_kernarg_size 520
		.amdhsa_user_sgpr_count 2
		.amdhsa_user_sgpr_dispatch_ptr 0
		.amdhsa_user_sgpr_queue_ptr 0
		.amdhsa_user_sgpr_kernarg_segment_ptr 1
		.amdhsa_user_sgpr_dispatch_id 0
		.amdhsa_user_sgpr_kernarg_preload_length 0
		.amdhsa_user_sgpr_kernarg_preload_offset 0
		.amdhsa_user_sgpr_private_segment_size 0
		.amdhsa_uses_dynamic_stack 0
		.amdhsa_enable_private_segment 0
		.amdhsa_system_sgpr_workgroup_id_x 1
		.amdhsa_system_sgpr_workgroup_id_y 0
		.amdhsa_system_sgpr_workgroup_id_z 0
		.amdhsa_system_sgpr_workgroup_info 0
		.amdhsa_system_vgpr_workitem_id 0
		.amdhsa_next_free_vgpr 255
		.amdhsa_next_free_sgpr 102
		.amdhsa_accum_offset 256
		.amdhsa_reserve_vcc 1
		.amdhsa_float_round_mode_32 0
		.amdhsa_float_round_mode_16_64 0
		.amdhsa_float_denorm_mode_32 3
		.amdhsa_float_denorm_mode_16_64 3
		.amdhsa_dx10_clamp 1
		.amdhsa_ieee_mode 1
		.amdhsa_fp16_overflow 0
		.amdhsa_tg_split 0
		.amdhsa_exception_fp_ieee_invalid_op 0
		.amdhsa_exception_fp_denorm_src 0
		.amdhsa_exception_fp_ieee_div_zero 0
		.amdhsa_exception_fp_ieee_overflow 0
		.amdhsa_exception_fp_ieee_underflow 0
		.amdhsa_exception_fp_ieee_inexact 0
		.amdhsa_exception_int_div_zero 0
	.end_amdhsa_kernel

; __global__ void __launch_bounds__(512, 2) fwd_kernel(Args args) {
amdhsa.kernels:
  - .agpr_count:     0
    .args:
      - .offset:         0
        .size:           264
        .value_kind:     by_value
      - .offset:         264
        .size:           4
        .value_kind:     hidden_block_count_x
      - .offset:         268
        .size:           4
        .value_kind:     hidden_block_count_y
      - .offset:         272
        .size:           4
        .value_kind:     hidden_block_count_z
      - .offset:         276
        .size:           2
        .value_kind:     hidden_group_size_x
      - .offset:         278
        .size:           2
        .value_kind:     hidden_group_size_y
      - .offset:         280
        .size:           2
        .value_kind:     hidden_group_size_z
      - .offset:         282
        .size:           2
        .value_kind:     hidden_remainder_x
      - .offset:         284
        .size:           2
        .value_kind:     hidden_remainder_y
      - .offset:         286
        .size:           2
        .value_kind:     hidden_remainder_z
      - .offset:         304
        .size:           8
        .value_kind:     hidden_global_offset_x
      - .offset:         312
        .size:           8
        .value_kind:     hidden_global_offset_y
      - .offset:         320
        .size:           8
        .value_kind:     hidden_global_offset_z
      - .offset:         328
        .size:           2
        .value_kind:     hidden_grid_dims
      - .offset:         384
        .size:           4
        .value_kind:     hidden_dynamic_lds_size
    .group_segment_fixed_size: 0
    .kernarg_segment_align: 8
    .kernarg_segment_size: 520
    .language:       OpenCL C
    .language_version:
      - 2
      - 0
    .max_flat_workgroup_size: 512
    .name:           _Z10fwd_kernel4Args
    .private_segment_fixed_size: 0
    .sgpr_count:     108
    .sgpr_spill_count: 173
    .symbol:         _Z10fwd_kernel4Args.kd
    .uniform_work_group_size: 1
    .uses_dynamic_stack: false
    .vgpr_count:     255
    .vgpr_spill_count: 0
    .wavefront_size: 64
